# v28 + P1 epilogue rs prefetch + epilogue packed-op split + attention DMA saddr + QK chain order (all individually neutral)
# baseline (speedup 1.0000x reference)
.LBB0_427:
	s_waitcnt vmcnt(0)
	v_mul_f32_e32 v126, v126, v152
	v_mul_f32_e32 v127, v127, v152
	v_lshlrev_b64 v[158:159], 7, v[146:147]
	v_mul_f32_e32 v147, 0xbfb8aa3b, v126
	v_exp_f32_e32 v147, v147
	v_mul_f32_e32 v157, 0xbfb8aa3b, v127
	v_exp_f32_e32 v157, v157
	v_mul_f32_e32 v160, v116, v152
	v_mul_f32_e32 v161, v117, v152
	v_add_f32_e32 v116, 1.0, v147
	v_rcp_f32_e32 v147, v116
	v_add_f32_e32 v116, 1.0, v157
	v_mul_f32_e32 v128, v128, v152
	v_mul_f32_e32 v129, v129, v152
	v_mul_f32_e32 v118, v118, v152
	v_mul_f32_e32 v119, v119, v152
	v_rcp_f32_e32 v157, v116
	v_mul_f32_e32 v116, v114, v152
	v_mul_f32_e32 v117, v115, v152
	v_mul_f32_e32 v114, v126, v147
	v_mul_f32_e32 v114, v118, v114
	v_mul_f32_e32 v118, 0xbfb8aa3b, v128
	v_mul_f32_e32 v126, 0xbfb8aa3b, v129
	v_exp_f32_e32 v118, v118
	v_exp_f32_e32 v126, v126
	v_mul_f32_e32 v115, v127, v157
	v_mul_f32_e32 v115, v119, v115
	v_add_f32_e32 v118, 1.0, v118
	v_add_f32_e32 v119, 1.0, v126
	v_rcp_f32_e32 v118, v118
	v_rcp_f32_e32 v119, v119
	v_mul_f32_e32 v122, v122, v152
	v_mul_f32_e32 v123, v123, v152
	v_mul_f32_e32 v120, v120, v152
	v_mul_f32_e32 v121, v121, v152
	v_cvt_pk_bf16_f32 v114, v114, v115
	v_mul_f32_e32 v115, v128, v118
	v_mul_f32_e32 v118, v129, v119
	v_mul_f32_e32 v119, 0xbfb8aa3b, v122
	v_mul_f32_e32 v115, v120, v115
	v_exp_f32_e32 v119, v119
	v_mul_f32_e32 v120, 0xbfb8aa3b, v123
	v_exp_f32_e32 v120, v120
	v_mul_f32_e32 v124, v124, v152
	v_mul_f32_e32 v125, v125, v152
	v_add_f32_e32 v119, 1.0, v119
	v_rcp_f32_e32 v119, v119
	v_add_f32_e32 v120, 1.0, v120
	v_rcp_f32_e32 v120, v120
	v_mul_f32_e32 v118, v121, v118
	v_cvt_pk_bf16_f32 v115, v115, v118
	v_mul_f32_e32 v118, v122, v119
	v_mul_f32_e32 v119, 0xbfb8aa3b, v124
	v_mul_f32_e32 v116, v116, v118
	v_mul_f32_e32 v118, v123, v120
	v_exp_f32_e32 v119, v119
	v_mul_f32_e32 v120, 0xbfb8aa3b, v125
	v_exp_f32_e32 v120, v120
	s_lshl_b32 s19, s26, 7
	s_or_b32 s19, s19, s43
	s_ashr_i32 s28, s19, 6
	v_mul_f32_e32 v117, v117, v118
	v_add_f32_e32 v118, 1.0, v119
	v_lshrrev_b32_e32 v148, 1, v148
	s_ashr_i32 s29, s28, 31
	v_rcp_f32_e32 v118, v118
	v_add_f32_e32 v119, 1.0, v120
	s_lshl_b64 s[28:29], s[28:29], 19
	v_and_or_b32 v148, v148, 24, s46
	v_rcp_f32_e32 v119, v119
	v_or_b32_e32 v148, s28, v148
	v_mov_b32_e32 v149, s29
	v_readlane_b32 s28, v245, 14
	v_readlane_b32 s29, v245, 15
	v_cvt_pk_bf16_f32 v116, v116, v117
	v_mul_f32_e32 v117, v124, v118
	v_mul_f32_e32 v117, v160, v117
	v_lshl_add_u64 v[158:159], s[28:29], 0, v[158:159]
	v_lshl_add_u64 v[158:159], v[148:149], 1, v[158:159]
	v_mul_f32_e32 v118, v125, v119
	v_mul_f32_e32 v118, v161, v118
	v_cvt_pk_bf16_f32 v117, v117, v118
	global_store_dwordx4 v[158:159], v[114:117], off
	s_and_b64 vcc, exec, s[8:9]
	s_nop 0
	v_or_b32_e32 v114, 16, v146
	v_ashrrev_i32_e32 v115, 31, v114
	s_cbranch_vccnz .LBB0_429
	v_readlane_b32 s28, v245, 16
	v_readlane_b32 s29, v245, 17
	s_nop 1
	v_lshl_add_u64 v[116:117], v[114:115], 2, s[28:29]
	v_mov_b32_e32 v150, v187
.LBB0_429:
	v_mul_f32_e32 v110, v110, v150
	v_mul_f32_e32 v111, v111, v150
	v_mul_f32_e32 v116, v100, v150
	v_mul_f32_e32 v117, v101, v150
	v_mul_f32_e32 v100, 0xbfb8aa3b, v110
	v_exp_f32_e32 v100, v100
	v_mul_f32_e32 v118, v98, v150
	v_mul_f32_e32 v119, v99, v150
	v_mul_f32_e32 v101, 0xbfb8aa3b, v111
	v_exp_f32_e32 v101, v101
	v_add_f32_e32 v98, 1.0, v100
	v_rcp_f32_e32 v99, v98
	v_mul_f32_e32 v112, v112, v150
	v_mul_f32_e32 v113, v113, v150
	v_mul_f32_e32 v102, v102, v150
	v_mul_f32_e32 v103, v103, v150
	v_add_f32_e32 v98, 1.0, v101
	v_mul_f32_e32 v99, v110, v99
	v_mul_f32_e32 v99, v102, v99
	v_mul_f32_e32 v101, 0xbfb8aa3b, v112
	v_mul_f32_e32 v102, 0xbfb8aa3b, v113
	v_exp_f32_e32 v101, v101
	v_exp_f32_e32 v102, v102
	v_rcp_f32_e32 v100, v98
	v_mul_f32_e32 v106, v106, v150
	v_mul_f32_e32 v107, v107, v150
	v_add_f32_e32 v101, 1.0, v101
	v_add_f32_e32 v102, 1.0, v102
	v_rcp_f32_e32 v101, v101
	v_rcp_f32_e32 v102, v102
	v_mul_f32_e32 v100, v111, v100
	v_mul_f32_e32 v100, v103, v100
	v_cvt_pk_bf16_f32 v100, v99, v100
	v_mul_f32_e32 v99, v112, v101
	v_mul_f32_e32 v101, v113, v102
	v_mul_f32_e32 v102, 0xbfb8aa3b, v106
	v_mul_f32_e32 v103, 0xbfb8aa3b, v107
	v_exp_f32_e32 v102, v102
	v_exp_f32_e32 v103, v103
	v_mul_f32_e32 v104, v104, v150
	v_mul_f32_e32 v105, v105, v150
	v_mul_f32_e32 v108, v108, v150
	v_mul_f32_e32 v109, v109, v150
	v_add_f32_e32 v102, 1.0, v102
	v_add_f32_e32 v103, 1.0, v103
	v_rcp_f32_e32 v102, v102
	v_rcp_f32_e32 v103, v103
	v_mul_f32_e32 v99, v104, v99
	v_mul_f32_e32 v101, v105, v101
	v_cvt_pk_bf16_f32 v101, v99, v101
	v_mul_f32_e32 v99, v106, v102
	v_mul_f32_e32 v102, v107, v103
	v_mul_f32_e32 v103, 0xbfb8aa3b, v108
	v_mul_f32_e32 v104, 0xbfb8aa3b, v109
	v_exp_f32_e32 v103, v103
	v_exp_f32_e32 v104, v104
	v_readlane_b32 s28, v245, 14
	v_lshlrev_b64 v[114:115], 7, v[114:115]
	v_add_f32_e32 v103, 1.0, v103
	v_add_f32_e32 v104, 1.0, v104
	v_rcp_f32_e32 v103, v103
	v_rcp_f32_e32 v104, v104
	v_readlane_b32 s29, v245, 15
	v_mul_f32_e32 v99, v118, v99
	v_mul_f32_e32 v102, v119, v102
	v_lshl_add_u64 v[114:115], s[28:29], 0, v[114:115]
	v_cvt_pk_bf16_f32 v102, v99, v102
	v_mul_f32_e32 v99, v108, v103
	v_mul_f32_e32 v103, v109, v104
	v_lshl_add_u64 v[114:115], v[148:149], 1, v[114:115]
	v_mul_f32_e32 v103, v117, v103
	v_mul_f32_e32 v99, v116, v99
	v_cvt_pk_bf16_f32 v103, v99, v103
	global_store_dwordx4 v[114:115], v[100:103], off
	v_mov_b32_e32 v98, 1.0
	s_and_b64 vcc, exec, s[8:9]
	v_or_b32_e32 v102, 32, v146
	v_ashrrev_i32_e32 v103, 31, v102
	v_mov_b32_e32 v100, 1.0
	s_cbranch_vccnz .LBB0_431
	v_readlane_b32 s28, v245, 16
	v_readlane_b32 s29, v245, 17
	s_nop 1
	v_lshl_add_u64 v[100:101], v[102:103], 2, s[28:29]
	v_mov_b32_e32 v100, v188
.LBB0_431:
	v_mul_f32_e32 v94, v94, v100
	v_mul_f32_e32 v95, v95, v100
	v_mul_f32_e32 v96, v96, v100
	v_mul_f32_e32 v97, v97, v100
	v_mul_f32_e32 v92, v92, v100
	v_mul_f32_e32 v93, v93, v100
	v_mul_f32_e32 v90, v90, v100
	v_mul_f32_e32 v91, v91, v100
	v_mul_f32_e32 v88, v88, v100
	v_mul_f32_e32 v89, v89, v100
	v_mul_f32_e32 v86, v86, v100
	v_mul_f32_e32 v87, v87, v100
	v_mul_f32_e32 v99, 0xbfb8aa3b, v94
	v_mul_f32_e32 v101, 0xbfb8aa3b, v95
	v_exp_f32_e32 v99, v99
	v_exp_f32_e32 v101, v101
	v_readlane_b32 s28, v245, 14
	v_lshlrev_b64 v[102:103], 7, v[102:103]
	v_readlane_b32 s29, v245, 15
	v_mul_f32_e32 v104, v84, v100
	v_mul_f32_e32 v105, v85, v100
	v_add_f32_e32 v84, 1.0, v99
	v_rcp_f32_e32 v99, v84
	v_add_f32_e32 v84, 1.0, v101
	v_rcp_f32_e32 v101, v84
	v_lshl_add_u64 v[102:103], s[28:29], 0, v[102:103]
	v_lshl_add_u64 v[102:103], v[148:149], 1, v[102:103]
	s_and_b64 vcc, exec, s[8:9]
	v_mul_f32_e32 v84, v82, v100
	v_mul_f32_e32 v85, v83, v100
	v_mul_f32_e32 v82, v94, v99
	v_mul_f32_e32 v82, v86, v82
	v_mul_f32_e32 v86, 0xbfb8aa3b, v96
	v_mul_f32_e32 v94, 0xbfb8aa3b, v97
	v_exp_f32_e32 v86, v86
	v_exp_f32_e32 v94, v94
	v_mul_f32_e32 v83, v95, v101
	v_mul_f32_e32 v83, v87, v83
	v_add_f32_e32 v86, 1.0, v86
	v_add_f32_e32 v87, 1.0, v94
	v_rcp_f32_e32 v86, v86
	v_rcp_f32_e32 v87, v87
	v_cvt_pk_bf16_f32 v82, v82, v83
	v_mul_f32_e32 v83, v96, v86
	v_mul_f32_e32 v86, v97, v87
	v_mul_f32_e32 v87, 0xbfb8aa3b, v90
	v_mul_f32_e32 v83, v88, v83
	v_exp_f32_e32 v87, v87
	v_mul_f32_e32 v88, 0xbfb8aa3b, v91
	v_exp_f32_e32 v88, v88
	v_mul_f32_e32 v86, v89, v86
	v_add_f32_e32 v87, 1.0, v87
	v_rcp_f32_e32 v87, v87
	v_add_f32_e32 v88, 1.0, v88
	v_rcp_f32_e32 v88, v88
	v_cvt_pk_bf16_f32 v83, v83, v86
	v_mul_f32_e32 v86, v90, v87
	v_mul_f32_e32 v87, 0xbfb8aa3b, v92
	v_mul_f32_e32 v84, v84, v86
	v_mul_f32_e32 v86, v91, v88
	v_exp_f32_e32 v87, v87
	v_mul_f32_e32 v88, 0xbfb8aa3b, v93
	v_exp_f32_e32 v88, v88
	v_mul_f32_e32 v85, v85, v86
	v_add_f32_e32 v86, 1.0, v87
	v_rcp_f32_e32 v86, v86
	v_add_f32_e32 v87, 1.0, v88
	v_rcp_f32_e32 v87, v87
	v_cvt_pk_bf16_f32 v84, v84, v85
	v_mul_f32_e32 v85, v92, v86
	v_mul_f32_e32 v85, v104, v85
	v_mul_f32_e32 v86, v93, v87
	v_mul_f32_e32 v86, v105, v86
	v_cvt_pk_bf16_f32 v85, v85, v86
	global_store_dwordx4 v[102:103], v[82:85], off
	s_nop 1
	v_or_b32_e32 v82, 48, v146
	v_ashrrev_i32_e32 v83, 31, v82
	s_cbranch_vccnz .LBB0_433
	v_readlane_b32 s28, v245, 16
	v_readlane_b32 s29, v245, 17
	s_nop 1
	v_lshl_add_u64 v[84:85], v[82:83], 2, s[28:29]
	v_mov_b32_e32 v98, v189
.LBB0_433:
	v_mul_f32_e32 v78, v78, v98
	v_mul_f32_e32 v79, v79, v98
	v_mul_f32_e32 v84, v68, v98
	v_mul_f32_e32 v85, v69, v98
	v_mul_f32_e32 v68, 0xbfb8aa3b, v78
	v_exp_f32_e32 v68, v68
	v_mul_f32_e32 v86, v66, v98
	v_mul_f32_e32 v87, v67, v98
	v_mul_f32_e32 v69, 0xbfb8aa3b, v79
	v_exp_f32_e32 v69, v69
	v_add_f32_e32 v66, 1.0, v68
	v_rcp_f32_e32 v67, v66
	v_mul_f32_e32 v80, v80, v98
	v_mul_f32_e32 v81, v81, v98
	v_mul_f32_e32 v70, v70, v98
	v_mul_f32_e32 v71, v71, v98
	v_add_f32_e32 v66, 1.0, v69
	v_mul_f32_e32 v67, v78, v67
	v_mul_f32_e32 v67, v70, v67
	v_mul_f32_e32 v69, 0xbfb8aa3b, v80
	v_mul_f32_e32 v70, 0xbfb8aa3b, v81
	v_exp_f32_e32 v69, v69
	v_exp_f32_e32 v70, v70
	v_rcp_f32_e32 v68, v66
	v_mul_f32_e32 v74, v74, v98
	v_mul_f32_e32 v75, v75, v98
	v_add_f32_e32 v69, 1.0, v69
	v_add_f32_e32 v70, 1.0, v70
	v_rcp_f32_e32 v69, v69
	v_rcp_f32_e32 v70, v70
	v_mul_f32_e32 v68, v79, v68
	v_mul_f32_e32 v68, v71, v68
	v_cvt_pk_bf16_f32 v68, v67, v68
	v_mul_f32_e32 v67, v80, v69
	v_mul_f32_e32 v69, v81, v70
	v_mul_f32_e32 v70, 0xbfb8aa3b, v74
	v_mul_f32_e32 v71, 0xbfb8aa3b, v75
	v_exp_f32_e32 v70, v70
	v_exp_f32_e32 v71, v71
	v_mul_f32_e32 v72, v72, v98
	v_mul_f32_e32 v73, v73, v98
	v_mul_f32_e32 v76, v76, v98
	v_mul_f32_e32 v77, v77, v98
	v_add_f32_e32 v70, 1.0, v70
	v_add_f32_e32 v71, 1.0, v71
	v_rcp_f32_e32 v70, v70
	v_rcp_f32_e32 v71, v71
	v_mul_f32_e32 v67, v72, v67
	v_mul_f32_e32 v69, v73, v69
	v_cvt_pk_bf16_f32 v69, v67, v69
	v_mul_f32_e32 v67, v74, v70
	v_mul_f32_e32 v70, v75, v71
	v_mul_f32_e32 v71, 0xbfb8aa3b, v76
	v_mul_f32_e32 v72, 0xbfb8aa3b, v77
	v_exp_f32_e32 v71, v71
	v_exp_f32_e32 v72, v72
	v_readlane_b32 s28, v245, 14
	v_lshlrev_b64 v[82:83], 7, v[82:83]
	v_add_f32_e32 v71, 1.0, v71
	v_add_f32_e32 v72, 1.0, v72
	v_rcp_f32_e32 v71, v71
	v_rcp_f32_e32 v72, v72
	v_readlane_b32 s29, v245, 15
	v_mul_f32_e32 v67, v86, v67
	v_mul_f32_e32 v70, v87, v70
	v_lshl_add_u64 v[82:83], s[28:29], 0, v[82:83]
	v_cvt_pk_bf16_f32 v70, v67, v70
	v_mul_f32_e32 v67, v76, v71
	v_mul_f32_e32 v71, v77, v72
	v_lshl_add_u64 v[82:83], v[148:149], 1, v[82:83]
	v_mul_f32_e32 v71, v85, v71
	v_mul_f32_e32 v67, v84, v67
	v_cvt_pk_bf16_f32 v71, v67, v71
	global_store_dwordx4 v[82:83], v[68:71], off
	v_mov_b32_e32 v66, 1.0
	s_and_b64 vcc, exec, s[8:9]
	v_add_u32_e32 v70, 0x80, v146
	v_ashrrev_i32_e32 v71, 31, v70
	v_mov_b32_e32 v68, 1.0
	s_cbranch_vccnz .LBB0_435
	v_readlane_b32 s28, v245, 16
	v_readlane_b32 s29, v245, 17
	s_nop 1
	v_lshl_add_u64 v[68:69], v[70:71], 2, s[28:29]
	v_mov_b32_e32 v68, v190
.LBB0_435:
	v_mul_f32_e32 v62, v62, v68
	v_mul_f32_e32 v63, v63, v68
	v_mul_f32_e32 v64, v64, v68
	v_mul_f32_e32 v65, v65, v68
	v_mul_f32_e32 v60, v60, v68
	v_mul_f32_e32 v61, v61, v68
	v_mul_f32_e32 v58, v58, v68
	v_mul_f32_e32 v59, v59, v68
	v_mul_f32_e32 v56, v56, v68
	v_mul_f32_e32 v57, v57, v68
	v_mul_f32_e32 v54, v54, v68
	v_mul_f32_e32 v55, v55, v68
	v_mul_f32_e32 v67, 0xbfb8aa3b, v62
	v_mul_f32_e32 v69, 0xbfb8aa3b, v63
	v_exp_f32_e32 v67, v67
	v_exp_f32_e32 v69, v69
	v_readlane_b32 s28, v245, 14
	v_lshlrev_b64 v[70:71], 7, v[70:71]
	v_readlane_b32 s29, v245, 15
	v_mul_f32_e32 v72, v52, v68
	v_mul_f32_e32 v73, v53, v68
	v_add_f32_e32 v52, 1.0, v67
	v_rcp_f32_e32 v67, v52
	v_add_f32_e32 v52, 1.0, v69
	v_rcp_f32_e32 v69, v52
	v_lshl_add_u64 v[70:71], s[28:29], 0, v[70:71]
	v_lshl_add_u64 v[70:71], v[148:149], 1, v[70:71]
	s_and_b64 vcc, exec, s[8:9]
	v_mul_f32_e32 v52, v50, v68
	v_mul_f32_e32 v53, v51, v68
	v_mul_f32_e32 v50, v62, v67
	v_mul_f32_e32 v50, v54, v50
	v_mul_f32_e32 v54, 0xbfb8aa3b, v64
	v_mul_f32_e32 v62, 0xbfb8aa3b, v65
	v_exp_f32_e32 v54, v54
	v_exp_f32_e32 v62, v62
	v_mul_f32_e32 v51, v63, v69
	v_mul_f32_e32 v51, v55, v51
	v_add_f32_e32 v54, 1.0, v54
	v_add_f32_e32 v55, 1.0, v62
	v_rcp_f32_e32 v54, v54
	v_rcp_f32_e32 v55, v55
	v_cvt_pk_bf16_f32 v50, v50, v51
	v_mul_f32_e32 v51, v64, v54
	v_mul_f32_e32 v54, v65, v55
	v_mul_f32_e32 v55, 0xbfb8aa3b, v58
	v_mul_f32_e32 v51, v56, v51
	v_exp_f32_e32 v55, v55
	v_mul_f32_e32 v56, 0xbfb8aa3b, v59
	v_exp_f32_e32 v56, v56
	v_mul_f32_e32 v54, v57, v54
	v_add_f32_e32 v55, 1.0, v55
	v_rcp_f32_e32 v55, v55
	v_add_f32_e32 v56, 1.0, v56
	v_rcp_f32_e32 v56, v56
	v_cvt_pk_bf16_f32 v51, v51, v54
	v_mul_f32_e32 v54, v58, v55
	v_mul_f32_e32 v55, 0xbfb8aa3b, v60
	v_mul_f32_e32 v52, v52, v54
	v_mul_f32_e32 v54, v59, v56
	v_exp_f32_e32 v55, v55
	v_mul_f32_e32 v56, 0xbfb8aa3b, v61
	v_exp_f32_e32 v56, v56
	v_mul_f32_e32 v53, v53, v54
	v_add_f32_e32 v54, 1.0, v55
	v_rcp_f32_e32 v54, v54
	v_add_f32_e32 v55, 1.0, v56
	v_rcp_f32_e32 v55, v55
	v_cvt_pk_bf16_f32 v52, v52, v53
	v_mul_f32_e32 v53, v60, v54
	v_mul_f32_e32 v53, v72, v53
	v_mul_f32_e32 v54, v61, v55
	v_mul_f32_e32 v54, v73, v54
	v_cvt_pk_bf16_f32 v53, v53, v54
	global_store_dwordx4 v[70:71], v[50:53], off
	s_nop 1
	v_add_u32_e32 v50, 0x90, v146
	v_ashrrev_i32_e32 v51, 31, v50
	s_cbranch_vccnz .LBB0_437
	v_readlane_b32 s28, v245, 16
	v_readlane_b32 s29, v245, 17
	s_nop 1
	v_lshl_add_u64 v[52:53], v[50:51], 2, s[28:29]
	v_mov_b32_e32 v66, v191
.LBB0_437:
	v_mul_f32_e32 v46, v46, v66
	v_mul_f32_e32 v47, v47, v66
	v_mul_f32_e32 v52, v36, v66
	v_mul_f32_e32 v53, v37, v66
	v_mul_f32_e32 v36, 0xbfb8aa3b, v46
	v_exp_f32_e32 v36, v36
	v_mul_f32_e32 v54, v34, v66
	v_mul_f32_e32 v55, v35, v66
	v_mul_f32_e32 v37, 0xbfb8aa3b, v47
	v_exp_f32_e32 v37, v37
	v_add_f32_e32 v34, 1.0, v36
	v_rcp_f32_e32 v35, v34
	v_mul_f32_e32 v48, v48, v66
	v_mul_f32_e32 v49, v49, v66
	v_mul_f32_e32 v38, v38, v66
	v_mul_f32_e32 v39, v39, v66
	v_add_f32_e32 v34, 1.0, v37
	v_mul_f32_e32 v35, v46, v35
	v_mul_f32_e32 v35, v38, v35
	v_mul_f32_e32 v37, 0xbfb8aa3b, v48
	v_mul_f32_e32 v38, 0xbfb8aa3b, v49
	v_exp_f32_e32 v37, v37
	v_exp_f32_e32 v38, v38
	v_rcp_f32_e32 v36, v34
	v_mul_f32_e32 v42, v42, v66
	v_mul_f32_e32 v43, v43, v66
	v_add_f32_e32 v37, 1.0, v37
	v_add_f32_e32 v38, 1.0, v38
	v_rcp_f32_e32 v37, v37
	v_rcp_f32_e32 v38, v38
	v_mul_f32_e32 v36, v47, v36
	v_mul_f32_e32 v36, v39, v36
	v_cvt_pk_bf16_f32 v36, v35, v36
	v_mul_f32_e32 v35, v48, v37
	v_mul_f32_e32 v37, v49, v38
	v_mul_f32_e32 v38, 0xbfb8aa3b, v42
	v_mul_f32_e32 v39, 0xbfb8aa3b, v43
	v_exp_f32_e32 v38, v38
	v_exp_f32_e32 v39, v39
	v_mul_f32_e32 v40, v40, v66
	v_mul_f32_e32 v41, v41, v66
	v_mul_f32_e32 v44, v44, v66
	v_mul_f32_e32 v45, v45, v66
	v_add_f32_e32 v38, 1.0, v38
	v_add_f32_e32 v39, 1.0, v39
	v_rcp_f32_e32 v38, v38
	v_rcp_f32_e32 v39, v39
	v_mul_f32_e32 v35, v40, v35
	v_mul_f32_e32 v37, v41, v37
	v_cvt_pk_bf16_f32 v37, v35, v37
	v_mul_f32_e32 v35, v42, v38
	v_mul_f32_e32 v38, v43, v39
	v_mul_f32_e32 v39, 0xbfb8aa3b, v44
	v_mul_f32_e32 v40, 0xbfb8aa3b, v45
	v_exp_f32_e32 v39, v39
	v_exp_f32_e32 v40, v40
	v_readlane_b32 s28, v245, 14
	v_lshlrev_b64 v[50:51], 7, v[50:51]
	v_add_f32_e32 v39, 1.0, v39
	v_add_f32_e32 v40, 1.0, v40
	v_rcp_f32_e32 v39, v39
	v_rcp_f32_e32 v40, v40
	v_readlane_b32 s29, v245, 15
	v_mul_f32_e32 v35, v54, v35
	v_mul_f32_e32 v38, v55, v38
	v_lshl_add_u64 v[50:51], s[28:29], 0, v[50:51]
	v_cvt_pk_bf16_f32 v38, v35, v38
	v_mul_f32_e32 v35, v44, v39
	v_mul_f32_e32 v39, v45, v40
	v_lshl_add_u64 v[50:51], v[148:149], 1, v[50:51]
	v_mul_f32_e32 v39, v53, v39
	v_mul_f32_e32 v35, v52, v35
	v_cvt_pk_bf16_f32 v39, v35, v39
	global_store_dwordx4 v[50:51], v[36:39], off
	v_mov_b32_e32 v34, 1.0
	s_and_b64 vcc, exec, s[8:9]
	v_add_u32_e32 v38, 0xa0, v146
	v_ashrrev_i32_e32 v39, 31, v38
	v_mov_b32_e32 v36, 1.0
	s_cbranch_vccnz .LBB0_439
	v_readlane_b32 s28, v245, 16
	v_readlane_b32 s29, v245, 17
	s_nop 1
	v_lshl_add_u64 v[36:37], v[38:39], 2, s[28:29]
	v_mov_b32_e32 v36, v192
.LBB0_439:
	v_mul_f32_e32 v30, v30, v36
	v_mul_f32_e32 v31, v31, v36
	v_mul_f32_e32 v32, v32, v36
	v_mul_f32_e32 v33, v33, v36
	v_mul_f32_e32 v28, v28, v36
	v_mul_f32_e32 v29, v29, v36
	v_mul_f32_e32 v26, v26, v36
	v_mul_f32_e32 v27, v27, v36
	v_mul_f32_e32 v24, v24, v36
	v_mul_f32_e32 v25, v25, v36
	v_mul_f32_e32 v22, v22, v36
	v_mul_f32_e32 v23, v23, v36
	v_mul_f32_e32 v35, 0xbfb8aa3b, v30
	v_mul_f32_e32 v37, 0xbfb8aa3b, v31
	v_exp_f32_e32 v35, v35
	v_exp_f32_e32 v37, v37
	v_readlane_b32 s28, v245, 14
	v_lshlrev_b64 v[38:39], 7, v[38:39]
	v_readlane_b32 s29, v245, 15
	v_mul_f32_e32 v40, v20, v36
	v_mul_f32_e32 v41, v21, v36
	v_add_f32_e32 v20, 1.0, v35
	v_rcp_f32_e32 v35, v20
	v_add_f32_e32 v20, 1.0, v37
	v_rcp_f32_e32 v37, v20
	v_lshl_add_u64 v[38:39], s[28:29], 0, v[38:39]
	v_lshl_add_u64 v[38:39], v[148:149], 1, v[38:39]
	s_and_b64 vcc, exec, s[8:9]
	v_mul_f32_e32 v20, v18, v36
	v_mul_f32_e32 v21, v19, v36
	v_mul_f32_e32 v18, v30, v35
	v_mul_f32_e32 v18, v22, v18
	v_mul_f32_e32 v22, 0xbfb8aa3b, v32
	v_mul_f32_e32 v30, 0xbfb8aa3b, v33
	v_exp_f32_e32 v22, v22
	v_exp_f32_e32 v30, v30
	v_mul_f32_e32 v19, v31, v37
	v_mul_f32_e32 v19, v23, v19
	v_add_f32_e32 v22, 1.0, v22
	v_add_f32_e32 v23, 1.0, v30
	v_rcp_f32_e32 v22, v22
	v_rcp_f32_e32 v23, v23
	v_cvt_pk_bf16_f32 v18, v18, v19
	v_mul_f32_e32 v19, v32, v22
	v_mul_f32_e32 v22, v33, v23
	v_mul_f32_e32 v23, 0xbfb8aa3b, v26
	v_mul_f32_e32 v19, v24, v19
	v_exp_f32_e32 v23, v23
	v_mul_f32_e32 v24, 0xbfb8aa3b, v27
	v_exp_f32_e32 v24, v24
	v_mul_f32_e32 v22, v25, v22
	v_add_f32_e32 v23, 1.0, v23
	v_rcp_f32_e32 v23, v23
	v_add_f32_e32 v24, 1.0, v24
	v_rcp_f32_e32 v24, v24
	v_cvt_pk_bf16_f32 v19, v19, v22
	v_mul_f32_e32 v22, v26, v23
	v_mul_f32_e32 v23, 0xbfb8aa3b, v28
	v_mul_f32_e32 v20, v20, v22
	v_mul_f32_e32 v22, v27, v24
	v_exp_f32_e32 v23, v23
	v_mul_f32_e32 v24, 0xbfb8aa3b, v29
	v_exp_f32_e32 v24, v24
	v_mul_f32_e32 v21, v21, v22
	v_add_f32_e32 v22, 1.0, v23
	v_rcp_f32_e32 v22, v22
	v_add_f32_e32 v23, 1.0, v24
	v_rcp_f32_e32 v23, v23
	v_cvt_pk_bf16_f32 v20, v20, v21
	v_mul_f32_e32 v21, v28, v22
	v_mul_f32_e32 v21, v40, v21
	v_mul_f32_e32 v22, v29, v23
	v_mul_f32_e32 v22, v41, v22
	v_cvt_pk_bf16_f32 v21, v21, v22
	global_store_dwordx4 v[38:39], v[18:21], off
	s_nop 1
	v_add_u32_e32 v18, 0xb0, v146
	v_ashrrev_i32_e32 v19, 31, v18
	s_cbranch_vccnz .LBB0_441
	v_readlane_b32 s8, v245, 16
	v_readlane_b32 s9, v245, 17
	s_nop 1
	v_lshl_add_u64 v[20:21], v[18:19], 2, s[8:9]
	v_mov_b32_e32 v34, v193
.LBB0_441:
	v_mul_f32_e32 v14, v14, v34
	v_mul_f32_e32 v15, v15, v34
	v_mul_f32_e32 v16, v16, v34
	v_mul_f32_e32 v17, v17, v34
	v_mul_f32_e32 v20, 0xbfb8aa3b, v14
	v_exp_f32_e32 v22, v20
	v_mul_f32_e32 v20, 0xbfb8aa3b, v15
	v_exp_f32_e32 v23, v20
	v_mul_f32_e32 v20, v4, v34
	v_mul_f32_e32 v21, v5, v34
	v_add_f32_e32 v4, 1.0, v22
	v_rcp_f32_e32 v22, v4
	v_add_f32_e32 v4, 1.0, v23
	v_mul_f32_e32 v6, v6, v34
	v_mul_f32_e32 v7, v7, v34
	v_rcp_f32_e32 v23, v4
	v_mul_f32_e32 v4, v2, v34
	v_mul_f32_e32 v5, v3, v34
	v_mul_f32_e32 v2, v14, v22
	v_mul_f32_e32 v2, v6, v2
	v_mul_f32_e32 v6, 0xbfb8aa3b, v16
	v_mul_f32_e32 v14, 0xbfb8aa3b, v17
	v_exp_f32_e32 v6, v6
	v_exp_f32_e32 v14, v14
	v_mul_f32_e32 v3, v15, v23
	v_mul_f32_e32 v3, v7, v3
	v_add_f32_e32 v6, 1.0, v6
	v_add_f32_e32 v7, 1.0, v14
	v_rcp_f32_e32 v6, v6
	v_rcp_f32_e32 v7, v7
	v_mul_f32_e32 v10, v10, v34
	v_mul_f32_e32 v11, v11, v34
	v_mul_f32_e32 v8, v8, v34
	v_mul_f32_e32 v9, v9, v34
	v_cvt_pk_bf16_f32 v2, v2, v3
	v_mul_f32_e32 v3, v16, v6
	v_mul_f32_e32 v6, v17, v7
	v_mul_f32_e32 v7, 0xbfb8aa3b, v10
	v_mul_f32_e32 v3, v8, v3
	v_exp_f32_e32 v7, v7
	v_mul_f32_e32 v8, 0xbfb8aa3b, v11
	v_exp_f32_e32 v8, v8
	v_mul_f32_e32 v12, v12, v34
	v_mul_f32_e32 v13, v13, v34
	v_add_f32_e32 v7, 1.0, v7
	v_rcp_f32_e32 v7, v7
	v_add_f32_e32 v8, 1.0, v8
	v_rcp_f32_e32 v8, v8
	v_mul_f32_e32 v6, v9, v6
	v_cvt_pk_bf16_f32 v3, v3, v6
	v_mul_f32_e32 v6, v10, v7
	v_mul_f32_e32 v7, 0xbfb8aa3b, v12
	v_mul_f32_e32 v4, v4, v6
	v_mul_f32_e32 v6, v11, v8
	v_exp_f32_e32 v7, v7
	v_mul_f32_e32 v8, 0xbfb8aa3b, v13
	v_exp_f32_e32 v8, v8
	v_mul_f32_e32 v5, v5, v6
	v_add_f32_e32 v6, 1.0, v7
	v_rcp_f32_e32 v6, v6
	v_add_f32_e32 v7, 1.0, v8
	v_rcp_f32_e32 v7, v7
	v_readlane_b32 s8, v245, 14
	v_lshlrev_b64 v[18:19], 7, v[18:19]
	v_readlane_b32 s9, v245, 15
	v_cvt_pk_bf16_f32 v4, v4, v5
	v_mul_f32_e32 v5, v12, v6
	v_mul_f32_e32 v5, v20, v5
	v_lshl_add_u64 v[18:19], s[8:9], 0, v[18:19]
	v_lshl_add_u64 v[18:19], v[148:149], 1, v[18:19]
	v_mul_f32_e32 v6, v13, v7
	s_andn2_b64 vcc, exec, s[6:7]
	s_mov_b64 s[6:7], -1
	v_mul_f32_e32 v6, v21, v6
	v_cvt_pk_bf16_f32 v5, v5, v6
	global_store_dwordx4 v[18:19], v[2:5], off
	s_cbranch_vccnz .LBB0_418
	s_andn2_b64 vcc, exec, s[2:3]
	s_cbranch_vccnz .LBB0_417
	s_barrier
	s_branch .LBB0_417
